# SIMD load balance: the second half-workgroup takes the mirrored block role (token block 3-lb in P5, query block 3-wq in attention) so each SIMD hosts a heavy and a light wave
# speedup vs baseline: 1.0214x; 1.0085x over previous
; #define LAS __attribute__((address_space(3)))
;     __device__ __forceinline__ PT() { out = (float*)(__attribute__((address_space(1))) float*)ptab_get(23); ws = (unsigned char*)(__attribute__((address_space(1))) unsigned char*)ptab_get(24); }
; __device__ __forceinline__ void phase_ssd_y(const PT& p, LAS unsigned char* lds, int tid, int lane, int wave) {
;     unsigned char* ws = p.ws; unsigned char* dob = (unsigned char*)p.out;
;     const int r32 = lane & 31, h = lane >> 5;
;     bf16* Ycat = (bf16*)(ws + WS_YCAT); const bf16* xT = (const bf16*)(ws + WS_XT); const bf16* Bn = (const bf16*)(dob + DO_BN); const bf16* Cn = (const bf16*)(ws + WS_CN);
;     const bf16* PV = (const bf16*)(dob + DO_PREV); const float* DT = (const float*)(ws + WS_DT);
;     LAS float* acum = (LAS float*)lds; LAS float* dtt = acum + 1024; LAS float* ssqp = dtt + 1024; LAS float* rsT = ssqp + 256;
;     LAS unsigned char* tile = lds + SY_TILE;
;     for (int it = blockIdx.x; it < 128 * 4; it += gridDim.x) {
;         const int bc = it >> 2, grp = it & 3, tok0 = bc * 128;
;         __syncthreads();
;         { const int hh = grp * 8 + wave; float d0, d1, c0, c1, tot; chunk_cumsum(DT, p.in[10], tok0, hh, lane, d0, d1, c0, c1, tot);
;           acum[wave * 128 + 2 * lane] = c0; acum[wave * 128 + 2 * lane + 1] = c1; dtt[wave * 128 + 2 * lane] = d0; dtt[wave * 128 + 2 * lane + 1] = d1; }
; #pragma unroll 4
;         for (int i = 0; i < 16; ++i) { const int pid = tid + 512 * i, row = pid >> 6, c8 = pid & 63;
;             *(LAS u32x4*)(tile + row * SY_TP + 16 * c8) = *(const u32x4*)(Ycat + ((size_t)tok0 + row) * 4096 + 2048 + grp * 512 + 8 * c8); }
;         __syncthreads();
;         const int pb = wave >> 2, lb = wave & 3, l = lb * 32 + r32; const size_t tok = (size_t)tok0 + l;
;         bf16x8 cf[8];
; #pragma unroll
;         for (int st = 0; st < 8; ++st) cf[st] = ld_frag16(Cn + tok * 512 + grp * 128 + 16 * st + 8 * h);
;     ...
;                         const int s0 = sb * 32 + 8 * qd + 4 * h;
;                         const f32x4 as = *(const LAS f32x4*)(acum + r * 128 + s0), ds = *(const LAS f32x4*)(dtt + r * 128 + s0);
; #pragma unroll
;                         for (int j = 0; j < 4; ++j) { const float v = X[sb][4 * qd + j] * __expf(al - as[j]) * ds[j]; mm[4 * qd + j] = (s0 + j < l) ? v : ((s0 + j == l) ? v + dsk : 0.f); }
.LBB0_482:
	s_or_b64 exec, exec, s[0:1]
	s_cmpk_lt_i32 s90, 0x200
	s_cselect_b64 s[0:1], -1, 0
	v_writelane_b32 v249, s0, 3
	s_waitcnt lgkmcnt(0)
	v_mov_b32_e32 v0, 0x23eb8
	v_mov_b32_e32 v2, 0x23ec0
	v_writelane_b32 v249, s1, 4
	v_writelane_b32 v249, s80, 5
	s_barrier
	s_nop 0
	v_writelane_b32 v249, s81, 6
	v_writelane_b32 v249, s84, 7
	ds_read_b64 v[0:1], v0
	s_nop 0
	v_writelane_b32 v249, s85, 8
	ds_read_b64 v[2:3], v2
	v_writelane_b32 v249, s86, 9
	v_bfe_u32 v117, v196, 8, 1
	v_mul_u32_u24_e32 v117, 0xc0, v117
	v_xor_b32_e32 v117, v196, v117
	s_waitcnt lgkmcnt(1)
	v_readfirstlane_b32 s83, v1
	v_writelane_b32 v249, s87, 10
	v_writelane_b32 v249, s88, 11
	v_writelane_b32 v249, s90, 12
	v_writelane_b32 v249, s89, 13
	v_readfirstlane_b32 s82, v0
	s_waitcnt lgkmcnt(0)
	v_readfirstlane_b32 s3, v3
	v_readfirstlane_b32 s2, v2
	s_cmpk_gt_i32 s90, 0x1ff
	v_readfirstlane_b32 s0, v117
	v_writelane_b32 v249, s92, 14
	s_nop 1
	v_writelane_b32 v249, s93, 15
	s_cbranch_scc1 .LBB0_515
	s_ashr_i32 s6, s0, 6
	s_add_u32 s88, s2, 0x6900000
	s_addc_u32 s89, s3, 0
	s_add_u32 s4, s2, 0x1e900000
	s_addc_u32 s5, s3, 0
	v_writelane_b32 v249, s4, 16
	v_and_b32_e32 v4, 63, v117
	v_mbcnt_hi_u32_b32 v6, -1, v182
	v_writelane_b32 v249, s5, 17
	s_add_u32 s4, s2, 0x100000
	s_addc_u32 s5, s3, 0
	v_writelane_b32 v249, s4, 18
	v_and_b32_e32 v7, 64, v6
	v_add_u32_e32 v0, -1, v6
	v_writelane_b32 v249, s5, 19
	v_cmp_eq_u32_e64 s[4:5], 0, v4
	v_cmp_lt_i32_e32 vcc, v0, v7
	v_bfe_u32 v5, v117, 5, 1
	v_writelane_b32 v249, s4, 20
	v_cndmask_b32_e32 v0, v0, v6, vcc
	v_lshlrev_b32_e32 v123, 2, v0
	v_writelane_b32 v249, s5, 21
	v_cmp_gt_u32_e64 s[4:5], 2, v4
	v_add_u32_e32 v0, -2, v6
	v_cmp_lt_i32_e32 vcc, v0, v7
	v_writelane_b32 v249, s4, 22
	v_mov_b32_e32 v121, 0
	v_cndmask_b32_e32 v0, v0, v6, vcc
	v_writelane_b32 v249, s5, 23
	v_cmp_gt_u32_e64 s[4:5], 4, v4
	v_lshlrev_b32_e32 v125, 2, v0
	v_add_u32_e32 v0, -4, v6
	v_writelane_b32 v249, s4, 24
	v_cmp_lt_i32_e32 vcc, v0, v7
	v_lshlrev_b32_e32 v126, 4, v5
	v_writelane_b32 v249, s5, 25
	v_cmp_gt_u32_e64 s[4:5], 8, v4
	v_mov_b32_e32 v127, v121
	v_cndmask_b32_e32 v0, v0, v6, vcc
	v_writelane_b32 v249, s4, 26
	s_ashr_i32 s1, s0, 8
	v_lshl_add_u64 v[2:3], s[82:83], 0, v[126:127]
	v_writelane_b32 v249, s5, 27
	v_cmp_gt_u32_e64 s[4:5], 16, v4
	v_lshlrev_b32_e32 v131, 2, v0
	v_add_u32_e32 v0, -8, v6
	v_writelane_b32 v249, s4, 28
	s_lshl_b32 s80, s1, 5
	v_and_b32_e32 v116, 31, v117
	v_writelane_b32 v249, s5, 29
	s_mov_b64 s[4:5], 0x6000000
	v_lshl_add_u64 v[128:129], v[2:3], 0, s[4:5]
	s_lshl_b32 s4, s1, 9
	v_cmp_lt_i32_e32 vcc, v0, v7
	s_and_b32 s0, s6, 3
	s_ashr_i32 s81, s80, 31
	s_add_i32 s4, s4, 0
	v_cndmask_b32_e32 v0, v0, v6, vcc
	v_lshl_or_b32 v124, s0, 5, v116
	s_cmp_lt_u32 s6, 4
	v_lshlrev_b32_e32 v133, 2, v0
	v_add_u32_e32 v0, -16, v6
	v_cmp_gt_u32_e64 s[94:95], 32, v4
	v_lshl_add_u32 v168, v124, 2, s4
	s_cselect_b64 s[4:5], -1, 0
	v_cmp_lt_i32_e32 vcc, v0, v7
	s_and_b64 s[4:5], s[94:95], s[4:5]
	v_writelane_b32 v249, s6, 30
	v_cndmask_b32_e32 v0, v0, v6, vcc
	s_cmp_lg_u32 s0, 0
	v_lshlrev_b32_e32 v135, 2, v0
	v_subrev_u32_e32 v0, 32, v6
	v_writelane_b32 v249, s4, 31
	s_mov_b32 s84, s90
	s_cselect_b64 s[90:91], -1, 0
	s_cmp_gt_u32 s0, 1
	v_cmp_lt_i32_e32 vcc, v0, v7
	v_xor_b32_e32 v2, 32, v6
	v_add_u32_e32 v3, 64, v7
	v_writelane_b32 v249, s5, 32
	s_cselect_b64 s[4:5], -1, 0
	v_cndmask_b32_e32 v0, v0, v6, vcc
	v_cmp_lt_i32_e32 vcc, v2, v3
	v_writelane_b32 v249, s4, 33
	s_cmp_eq_u32 s0, 3
	v_lshlrev_b32_e32 v18, 2, v5
	v_cndmask_b32_e32 v2, v6, v2, vcc
	v_writelane_b32 v249, s5, 34
	s_cselect_b64 s[4:5], -1, 0
	v_or_b32_e32 v6, 18, v18
	v_or_b32_e32 v7, 26, v18
	v_writelane_b32 v249, s4, 35
	v_cmp_lt_u32_e64 s[58:59], v6, v124
	v_cmp_eq_u32_e64 s[62:63], v6, v124
	v_or_b32_e32 v6, 25, v18
	v_cmp_lt_u32_e64 s[74:75], v7, v124
	v_cmp_eq_u32_e64 s[78:79], v7, v124
	v_or_b32_e32 v7, 33, v18
	v_writelane_b32 v249, s5, 36
	v_cmp_lt_u32_e64 s[64:65], v6, v124
	v_cmp_eq_u32_e64 s[68:69], v6, v124
	v_or_b32_e32 v6, 27, v18
	v_cmp_lt_u32_e64 s[4:5], v7, v124
	v_cmp_lt_u32_e64 s[72:73], v6, v124
	v_cmp_eq_u32_e64 s[76:77], v6, v124
	v_or_b32_e32 v6, 32, v18
	v_writelane_b32 v249, s4, 37
	v_or_b32_e32 v8, 34, v18
	v_or_b32_e32 v9, 42, v18
	v_writelane_b32 v249, s5, 38
	v_cmp_lt_u32_e64 s[4:5], v6, v124
	v_or_b32_e32 v10, 50, v18
	v_or_b32_e32 v11, 58, v18
	v_writelane_b32 v249, s4, 39
	v_cmp_lt_u32_e64 s[8:9], v11, v124
	v_cmp_eq_u32_e64 s[12:13], v11, v124
	v_writelane_b32 v249, s5, 40
	v_cmp_eq_u32_e64 s[4:5], v7, v124
	v_or_b32_e32 v7, 35, v18
	v_or_b32_e32 v11, 0x41, v18
	v_writelane_b32 v249, s4, 41
	v_lshlrev_b32_e32 v118, 3, v4
	v_cmp_lt_u32_e64 s[92:93], v11, v124
	v_writelane_b32 v249, s5, 42
	v_cmp_eq_u32_e64 s[4:5], v6, v124
	v_lshlrev_b32_e32 v166, 2, v0
	v_lshl_or_b32 v0, s6, 9, v118
	v_writelane_b32 v249, s4, 43
	v_or_b32_e32 v12, 0x42, v18
	v_or_b32_e32 v13, 0x4a, v18
	v_writelane_b32 v249, s5, 44
	v_cmp_lt_u32_e64 s[4:5], v7, v124
	v_or_b32_e32 v14, 0x52, v18
	v_or_b32_e32 v15, 0x5a, v18
	v_writelane_b32 v249, s4, 45
	v_or_b32_e32 v16, 0x62, v18
	v_or_b32_e32 v17, 0x6a, v18
	v_writelane_b32 v249, s5, 46
	v_cmp_lt_u32_e64 s[4:5], v8, v124
	v_or_b32_e32 v19, 0x72, v18
	v_lshlrev_b32_e32 v119, 1, v4
	v_writelane_b32 v249, s4, 47
	v_add_u32_e32 v167, 0, v0
	v_lshl_add_u32 v122, v4, 4, 0
	v_writelane_b32 v249, s5, 48
	v_cmp_eq_u32_e64 s[4:5], v7, v124
	v_or_b32_e32 v7, 40, v18
	v_lshlrev_b32_e32 v0, 3, v5
	v_writelane_b32 v249, s4, 49
	v_or_b32_e32 v130, 32, v4
	v_or_b32_e32 v134, 0x60, v4
	v_writelane_b32 v249, s5, 50
	v_cmp_eq_u32_e64 s[4:5], v8, v124
	v_or_b32_e32 v8, 41, v18
	v_or_b32_e32 v4, 2, v18
	v_writelane_b32 v249, s4, 51
; #define LAS __attribute__((address_space(3)))
; __device__ __forceinline__ void phase_ssd_y(const PT& p, LAS unsigned char* lds, int tid, int lane, int wave) {
;     ...
;                         const int s0 = sb * 32 + 8 * qd + 4 * h;
;                         const f32x4 as = *(const LAS f32x4*)(acum + r * 128 + s0), ds = *(const LAS f32x4*)(dtt + r * 128 + s0);
; #pragma unroll
;                         for (int j = 0; j < 4; ++j) { const float v = X[sb][4 * qd + j] * __expf(al - as[j]) * ds[j]; mm[4 * qd + j] = (s0 + j < l) ? v : ((s0 + j == l) ? v + dsk : 0.f); }
	v_or_b32_e32 v5, 10, v18
	v_or_b32_e32 v3, 1, v18
	v_writelane_b32 v249, s5, 52
	v_cmp_lt_u32_e64 s[4:5], v8, v124
	v_cmp_lt_u32_e64 s[24:25], v4, v124
	v_cmp_eq_u32_e64 s[28:29], v4, v124
	v_writelane_b32 v249, s4, 53
	v_or_b32_e32 v4, 9, v18
	v_cmp_lt_u32_e64 s[42:43], v5, v124
	v_writelane_b32 v249, s5, 54
	v_cmp_lt_u32_e64 s[4:5], v7, v124
	v_cmp_eq_u32_e64 s[46:47], v5, v124
	v_or_b32_e32 v5, 17, v18
	v_writelane_b32 v249, s4, 55
	v_cmp_lt_u32_e64 s[14:15], v3, v124
	v_cmp_eq_u32_e64 s[18:19], v3, v124
	v_writelane_b32 v249, s5, 56
	v_cmp_eq_u32_e64 s[4:5], v8, v124
	v_or_b32_e32 v8, 43, v18
	v_or_b32_e32 v3, 3, v18
	v_writelane_b32 v249, s4, 57
	v_cmp_lt_u32_e64 s[30:31], v4, v124
	v_cmp_eq_u32_e64 s[36:37], v4, v124
	v_writelane_b32 v249, s5, 58
	v_cmp_eq_u32_e64 s[4:5], v7, v124
	v_or_b32_e32 v4, 11, v18
	v_cmp_lt_u32_e64 s[48:49], v5, v124
	v_writelane_b32 v249, s4, 59
	v_cmp_eq_u32_e64 s[52:53], v5, v124
	v_or_b32_e32 v5, 19, v18
	v_writelane_b32 v249, s5, 60
	v_cmp_lt_u32_e64 s[4:5], v8, v124
	v_cmp_lt_u32_e64 s[16:17], v18, v124
	v_cmp_eq_u32_e64 s[20:21], v18, v124
	v_writelane_b32 v249, s4, 61
	v_cmp_lt_u32_e64 s[22:23], v3, v124
	v_cmp_eq_u32_e64 s[26:27], v3, v124
	v_writelane_b32 v249, s5, 62
	v_cmp_lt_u32_e64 s[4:5], v9, v124
	v_or_b32_e32 v3, 8, v18
	v_cmp_lt_u32_e64 s[40:41], v4, v124
	v_writelane_b32 v249, s4, 63
	v_cmp_eq_u32_e64 s[44:45], v4, v124
	v_or_b32_e32 v4, 16, v18
	v_writelane_b32 v248, s5, 0
	v_cmp_eq_u32_e64 s[4:5], v8, v124
	v_or_b32_e32 v8, 48, v18
	v_cmp_lt_u32_e64 s[56:57], v5, v124
	v_writelane_b32 v248, s4, 1
	v_cmp_eq_u32_e64 s[60:61], v5, v124
	v_or_b32_e32 v5, 24, v18
	v_writelane_b32 v248, s5, 2
	v_cmp_eq_u32_e64 s[4:5], v9, v124
	v_or_b32_e32 v9, 49, v18
	s_lshl_b32 s1, s1, 6
	v_writelane_b32 v248, s4, 3
	s_movk_i32 s33, 0x410
	v_mad_u32_u24 v1, v124, s33, 0
	v_writelane_b32 v248, s5, 4
	v_cmp_lt_u32_e64 s[4:5], v9, v124
	v_lshlrev_b32_e32 v127, 2, v2
	v_mul_i32_i24_e32 v2, 0xfffffbf4, v124
	v_writelane_b32 v248, s4, 5
	v_cmp_lt_u32_e64 s[34:35], v3, v124
	v_cmp_eq_u32_e64 s[38:39], v3, v124
	v_writelane_b32 v248, s5, 6
	v_cmp_lt_u32_e64 s[4:5], v8, v124
	v_lshlrev_b32_e32 v185, 2, v3
	v_lshlrev_b32_e32 v3, 2, v116
	v_writelane_b32 v248, s4, 7
	s_mov_b32 s97, 0
	v_or_b32_e32 v132, 64, v116
	v_writelane_b32 v248, s5, 8
	v_cmp_eq_u32_e64 s[4:5], v9, v124
	v_or_b32_e32 v9, 51, v18
	v_cmp_lt_u32_e64 s[50:51], v4, v124
	v_writelane_b32 v248, s4, 9
	v_cmp_eq_u32_e64 s[54:55], v4, v124
	v_cmp_lt_u32_e64 s[66:67], v5, v124
	v_writelane_b32 v248, s5, 10
	v_cmp_eq_u32_e64 s[4:5], v8, v124
	v_cmp_eq_u32_e64 s[70:71], v5, v124
	v_lshlrev_b32_e32 v179, 2, v8
	v_writelane_b32 v248, s4, 11
	v_lshlrev_b32_e32 v180, 2, v7
	v_lshlrev_b32_e32 v181, 2, v6
	v_writelane_b32 v248, s5, 12
	v_cmp_lt_u32_e64 s[4:5], v9, v124
	v_lshlrev_b32_e32 v183, 2, v5
	v_lshlrev_b32_e32 v184, 2, v4
	v_writelane_b32 v248, s4, 13
	v_lshl_or_b32 v186, s0, 7, v3
	v_mov_b32_e32 v187, 0x23e50
	v_writelane_b32 v248, s5, 14
	v_cmp_lt_u32_e64 s[4:5], v10, v124
	v_lshlrev_b32_e32 v120, 1, v118
	s_movk_i32 s0, 0x1000
	v_writelane_b32 v248, s4, 15
	v_lshlrev_b32_e32 v140, 1, v0
	v_mov_b32_e32 v188, 0x23e58
	v_writelane_b32 v248, s5, 16
	v_cmp_eq_u32_e64 s[4:5], v9, v124
	v_or_b32_e32 v9, 56, v18
	v_lshlrev_b32_e32 v178, 2, v9
	v_writelane_b32 v248, s4, 17
	v_add_u32_e32 v189, v1, v2
	v_mov_b32_e32 v190, 0x3727c5ac
	v_writelane_b32 v248, s5, 18
	v_cmp_eq_u32_e64 s[4:5], v10, v124
	v_or_b32_e32 v10, 57, v18
	v_cmp_eq_u32_e64 s[86:87], v10, v124
	v_writelane_b32 v248, s4, 19
	v_mov_b32_e32 v191, 0x23e60
	s_nop 0
	v_writelane_b32 v248, s5, 20
	v_cmp_lt_u32_e64 s[4:5], v10, v124
	v_or_b32_e32 v10, 59, v18
	v_cmp_lt_u32_e64 s[6:7], v10, v124
	v_writelane_b32 v248, s4, 21
	v_cmp_eq_u32_e64 s[10:11], v10, v124
	v_or_b32_e32 v10, 64, v18
	v_writelane_b32 v248, s5, 22
	v_cmp_lt_u32_e64 s[4:5], v9, v124
	v_lshlrev_b32_e32 v177, 2, v10
	s_nop 0
	v_writelane_b32 v248, s4, 23
	s_nop 1
	v_writelane_b32 v248, s5, 24
	v_writelane_b32 v248, s92, 25
	v_cmp_eq_u32_e64 s[4:5], v9, v124
	s_nop 0
	v_writelane_b32 v248, s93, 26
	v_cmp_lt_u32_e64 s[92:93], v10, v124
	s_nop 1
	v_writelane_b32 v248, s92, 27
	s_nop 1
	v_writelane_b32 v248, s93, 28
	v_cmp_eq_u32_e64 s[92:93], v11, v124
	v_or_b32_e32 v11, 0x43, v18
	s_nop 0
	v_writelane_b32 v248, s92, 29
	s_nop 1
	v_writelane_b32 v248, s93, 30
	v_cmp_eq_u32_e64 s[92:93], v10, v124
	s_nop 1
	v_writelane_b32 v248, s92, 31
	s_nop 1
	v_writelane_b32 v248, s93, 32
	v_cmp_lt_u32_e64 s[92:93], v11, v124
	s_nop 1
	v_writelane_b32 v248, s92, 33
	s_nop 1
	v_writelane_b32 v248, s93, 34
	v_cmp_lt_u32_e64 s[92:93], v12, v124
	s_nop 1
	v_writelane_b32 v248, s92, 35
	s_nop 1
	v_writelane_b32 v248, s93, 36
	v_cmp_eq_u32_e64 s[92:93], v11, v124
	v_or_b32_e32 v11, 0x48, v18
	v_lshlrev_b32_e32 v176, 2, v11
	v_writelane_b32 v248, s92, 37
	s_nop 1
	v_writelane_b32 v248, s93, 38
	v_cmp_eq_u32_e64 s[92:93], v12, v124
	v_or_b32_e32 v12, 0x49, v18
	s_nop 0
	v_writelane_b32 v248, s92, 39
	s_nop 1
	v_writelane_b32 v248, s93, 40
	v_cmp_lt_u32_e64 s[92:93], v12, v124
	s_nop 1
	v_writelane_b32 v248, s92, 41
	s_nop 1
	v_writelane_b32 v248, s93, 42
	v_cmp_lt_u32_e64 s[92:93], v11, v124
	s_nop 1
	v_writelane_b32 v248, s92, 43
	s_nop 1
	v_writelane_b32 v248, s93, 44
	v_cmp_eq_u32_e64 s[92:93], v12, v124
	v_or_b32_e32 v12, 0x4b, v18
	s_nop 0
	v_writelane_b32 v248, s92, 45
	s_nop 1
	v_writelane_b32 v248, s93, 46
	v_cmp_eq_u32_e64 s[92:93], v11, v124
	s_nop 1
	v_writelane_b32 v248, s92, 47
	s_nop 1
	v_writelane_b32 v248, s93, 48
	v_cmp_lt_u32_e64 s[92:93], v12, v124
	s_nop 1
	v_writelane_b32 v248, s92, 49
	s_nop 1
	v_writelane_b32 v248, s93, 50
; #define LAS __attribute__((address_space(3)))
; __device__ __forceinline__ void phase_ssd_y(const PT& p, LAS unsigned char* lds, int tid, int lane, int wave) {
;     ...
;                         const int s0 = sb * 32 + 8 * qd + 4 * h;
;                         const f32x4 as = *(const LAS f32x4*)(acum + r * 128 + s0), ds = *(const LAS f32x4*)(dtt + r * 128 + s0);
; #pragma unroll
;                         for (int j = 0; j < 4; ++j) { const float v = X[sb][4 * qd + j] * __expf(al - as[j]) * ds[j]; mm[4 * qd + j] = (s0 + j < l) ? v : ((s0 + j == l) ? v + dsk : 0.f); }
	v_cmp_lt_u32_e64 s[92:93], v13, v124
	s_nop 1
	v_writelane_b32 v248, s92, 51
	s_nop 1
	v_writelane_b32 v248, s93, 52
	v_cmp_eq_u32_e64 s[92:93], v12, v124
	v_or_b32_e32 v12, 0x50, v18
	v_lshlrev_b32_e32 v175, 2, v12
	v_writelane_b32 v248, s92, 53
	s_nop 1
	v_writelane_b32 v248, s93, 54
	v_cmp_eq_u32_e64 s[92:93], v13, v124
	v_or_b32_e32 v13, 0x51, v18
	s_nop 0
	v_writelane_b32 v248, s92, 55
	s_nop 1
	v_writelane_b32 v248, s93, 56
	v_cmp_lt_u32_e64 s[92:93], v13, v124
	s_nop 1
	v_writelane_b32 v248, s92, 57
	s_nop 1
	v_writelane_b32 v248, s93, 58
	v_cmp_lt_u32_e64 s[92:93], v12, v124
	s_nop 1
	v_writelane_b32 v248, s92, 59
	s_nop 1
	v_writelane_b32 v248, s93, 60
	v_cmp_eq_u32_e64 s[92:93], v13, v124
	v_or_b32_e32 v13, 0x53, v18
	s_nop 0
	v_writelane_b32 v248, s92, 61
	s_nop 1
	v_writelane_b32 v248, s93, 62
	v_cmp_eq_u32_e64 s[92:93], v12, v124
	s_nop 1
	v_writelane_b32 v248, s92, 63
	s_nop 1
	v_writelane_b32 v247, s93, 0
	v_cmp_lt_u32_e64 s[92:93], v13, v124
	s_nop 1
	v_writelane_b32 v247, s92, 1
	s_nop 1
	v_writelane_b32 v247, s93, 2
	v_cmp_lt_u32_e64 s[92:93], v14, v124
	s_nop 1
	v_writelane_b32 v247, s92, 3
	s_nop 1
	v_writelane_b32 v247, s93, 4
	v_cmp_eq_u32_e64 s[92:93], v13, v124
	v_or_b32_e32 v13, 0x58, v18
	v_lshlrev_b32_e32 v174, 2, v13
	v_writelane_b32 v247, s92, 5
	s_nop 1
	v_writelane_b32 v247, s93, 6
	v_cmp_eq_u32_e64 s[92:93], v14, v124
	v_or_b32_e32 v14, 0x59, v18
	s_nop 0
	v_writelane_b32 v247, s92, 7
	s_nop 1
	v_writelane_b32 v247, s93, 8
	v_cmp_lt_u32_e64 s[92:93], v14, v124
	s_nop 1
	v_writelane_b32 v247, s92, 9
	s_nop 1
	v_writelane_b32 v247, s93, 10
	v_cmp_lt_u32_e64 s[92:93], v13, v124
	s_nop 1
	v_writelane_b32 v247, s92, 11
	s_nop 1
	v_writelane_b32 v247, s93, 12
	v_cmp_eq_u32_e64 s[92:93], v14, v124
	v_or_b32_e32 v14, 0x5b, v18
	s_nop 0
	v_writelane_b32 v247, s92, 13
	s_nop 1
	v_writelane_b32 v247, s93, 14
	v_cmp_eq_u32_e64 s[92:93], v13, v124
	s_nop 1
	v_writelane_b32 v247, s92, 15
	s_nop 1
	v_writelane_b32 v247, s93, 16
	v_cmp_lt_u32_e64 s[92:93], v14, v124
	s_nop 1
	v_writelane_b32 v247, s92, 17
	s_nop 1
	v_writelane_b32 v247, s93, 18
	v_cmp_lt_u32_e64 s[92:93], v15, v124
	s_nop 1
	v_writelane_b32 v247, s92, 19
	s_nop 1
	v_writelane_b32 v247, s93, 20
	v_cmp_eq_u32_e64 s[92:93], v14, v124
	v_or_b32_e32 v14, 0x60, v18
	v_lshlrev_b32_e32 v173, 2, v14
	v_writelane_b32 v247, s92, 21
	s_nop 1
	v_writelane_b32 v247, s93, 22
	v_cmp_eq_u32_e64 s[92:93], v15, v124
	v_or_b32_e32 v15, 0x61, v18
	s_nop 0
	v_writelane_b32 v247, s92, 23
	s_nop 1
	v_writelane_b32 v247, s93, 24
	v_cmp_lt_u32_e64 s[92:93], v15, v124
	s_nop 1
	v_writelane_b32 v247, s92, 25
	s_nop 1
	v_writelane_b32 v247, s93, 26
	v_cmp_lt_u32_e64 s[92:93], v14, v124
	s_nop 1
	v_writelane_b32 v247, s92, 27
	s_nop 1
	v_writelane_b32 v247, s93, 28
	v_cmp_eq_u32_e64 s[92:93], v15, v124
	v_or_b32_e32 v15, 0x63, v18
	s_nop 0
	v_writelane_b32 v247, s92, 29
	s_nop 1
	v_writelane_b32 v247, s93, 30
	v_cmp_eq_u32_e64 s[92:93], v14, v124
	s_nop 1
	v_writelane_b32 v247, s92, 31
	s_nop 1
	v_writelane_b32 v247, s93, 32
	v_cmp_lt_u32_e64 s[92:93], v15, v124
	s_nop 1
	v_writelane_b32 v247, s92, 33
	s_nop 1
	v_writelane_b32 v247, s93, 34
	v_cmp_lt_u32_e64 s[92:93], v16, v124
	s_nop 1
	v_writelane_b32 v247, s92, 35
	s_nop 1
	v_writelane_b32 v247, s93, 36
	v_cmp_eq_u32_e64 s[92:93], v15, v124
	v_or_b32_e32 v15, 0x68, v18
	v_lshlrev_b32_e32 v172, 2, v15
	v_writelane_b32 v247, s92, 37
	s_nop 1
	v_writelane_b32 v247, s93, 38
	v_cmp_eq_u32_e64 s[92:93], v16, v124
	v_or_b32_e32 v16, 0x69, v18
	s_nop 0
	v_writelane_b32 v247, s92, 39
	s_nop 1
	v_writelane_b32 v247, s93, 40
	v_cmp_lt_u32_e64 s[92:93], v16, v124
; #define LAS __attribute__((address_space(3)))
; __device__ __forceinline__ f32x16 mfma32(bf16x8 a, bf16x8 b, f32x16 c) { return __builtin_amdgcn_mfma_f32_32x32x16_bf16(a, b, c, 0, 0, 0); }
; __device__ __forceinline__ void phase_ssd_y(const PT& p, LAS unsigned char* lds, int tid, int lane, int wave) {
;     ...
;             const bf16* pp = PV + ((size_t)(bc * 32 + hh) * 64 + pb * 32 + r32) * 128 + 8 * h;
; #pragma unroll
;             for (int st = 0; st < 8; ++st) acc = mfma32(ld_frag16(pp + 16 * st), cf[st], acc);
;             const float al = acum[r * 128 + l]; const float el = __expf(al); const float dsk = p.in[11][hh];
; #pragma unroll
;             for (int i = 0; i < 16; ++i) acc[i] *= el;
;             const bf16* xrow = xT + ((size_t)bc * 2048 + hh * 64 + pb * 32 + r32) * 128 + 4 * h;
; #pragma unroll
;             for (int sb = 0; sb < 4; ++sb) {
;                 if (sb <= lb) {
;                     f32x16 mm;
; #pragma unroll
;                     for (int qd = 0; qd < 4; ++qd) {
;                         const int s0 = sb * 32 + 8 * qd + 4 * h;
;                         const f32x4 as = *(const LAS f32x4*)(acum + r * 128 + s0), ds = *(const LAS f32x4*)(dtt + r * 128 + s0);
; #pragma unroll
;                         for (int j = 0; j < 4; ++j) { const float v = X[sb][4 * qd + j] * __expf(al - as[j]) * ds[j]; mm[4 * qd + j] = (s0 + j < l) ? v : ((s0 + j == l) ? v + dsk : 0.f); }
;                     }
; #pragma unroll
;                     for (int s2 = 0; s2 < 2; ++s2) acc = mfma32(ld_frag8x2(xrow + sb * 32 + 16 * s2), pack_frag(mm, s2), acc);
;                 }
;             }
; #pragma unroll
;             for (int qd = 0; qd < 4; ++qd) {
;                 LAS u32x2* yp = (LAS u32x2*)(tile + l * SY_TP + (r * 64 + pb * 32 + 8 * qd + 4 * h) * 2); const u32x2 zz = *yp;
	s_nop 1
	v_writelane_b32 v247, s92, 41
	s_nop 1
	v_writelane_b32 v247, s93, 42
	v_cmp_lt_u32_e64 s[92:93], v15, v124
	s_nop 1
	v_writelane_b32 v247, s92, 43
	s_nop 1
	v_writelane_b32 v247, s93, 44
	v_cmp_eq_u32_e64 s[92:93], v16, v124
	v_or_b32_e32 v16, 0x6b, v18
	s_nop 0
	v_writelane_b32 v247, s92, 45
	s_nop 1
	v_writelane_b32 v247, s93, 46
	v_cmp_eq_u32_e64 s[92:93], v15, v124
	s_nop 1
	v_writelane_b32 v247, s92, 47
	s_nop 1
	v_writelane_b32 v247, s93, 48
	v_cmp_lt_u32_e64 s[92:93], v16, v124
	s_nop 1
	v_writelane_b32 v247, s92, 49
	s_nop 1
	v_writelane_b32 v247, s93, 50
	v_cmp_lt_u32_e64 s[92:93], v17, v124
	s_nop 1
	v_writelane_b32 v247, s92, 51
	s_nop 1
	v_writelane_b32 v247, s93, 52
	v_cmp_eq_u32_e64 s[92:93], v16, v124
	v_or_b32_e32 v16, 0x70, v18
	v_lshlrev_b32_e32 v171, 2, v16
	v_writelane_b32 v247, s92, 53
	s_nop 1
	v_writelane_b32 v247, s93, 54
	v_cmp_eq_u32_e64 s[92:93], v17, v124
	v_or_b32_e32 v17, 0x71, v18
	s_nop 0
	v_writelane_b32 v247, s92, 55
	s_nop 1
	v_writelane_b32 v247, s93, 56
	v_cmp_lt_u32_e64 s[92:93], v17, v124
	s_nop 1
	v_writelane_b32 v247, s92, 57
	s_nop 1
	v_writelane_b32 v247, s93, 58
	v_cmp_lt_u32_e64 s[92:93], v16, v124
	s_nop 1
	v_writelane_b32 v247, s92, 59
	s_nop 1
	v_writelane_b32 v247, s93, 60
	v_cmp_eq_u32_e64 s[92:93], v17, v124
	v_or_b32_e32 v17, 0x73, v18
	s_nop 0
	v_writelane_b32 v247, s92, 61
	s_nop 1
	v_writelane_b32 v247, s93, 62
	v_cmp_eq_u32_e64 s[92:93], v16, v124
	s_nop 1
	v_writelane_b32 v247, s92, 63
	s_nop 1
	v_writelane_b32 v246, s93, 0
	v_cmp_lt_u32_e64 s[92:93], v17, v124
	s_nop 1
	v_writelane_b32 v246, s92, 1
	s_nop 1
	v_writelane_b32 v246, s93, 2
	v_cmp_lt_u32_e64 s[92:93], v19, v124
	s_nop 1
	v_writelane_b32 v246, s92, 3
	s_nop 1
	v_writelane_b32 v246, s93, 4
	v_cmp_eq_u32_e64 s[92:93], v17, v124
	v_or_b32_e32 v17, 0x78, v18
	v_lshlrev_b32_e32 v170, 2, v17
	v_writelane_b32 v246, s92, 5
	s_nop 1
	v_writelane_b32 v246, s93, 6
	v_cmp_eq_u32_e64 s[92:93], v19, v124
	v_or_b32_e32 v19, 0x79, v18
	s_nop 0
	v_writelane_b32 v246, s92, 7
	s_nop 1
	v_writelane_b32 v246, s93, 8
	v_cmp_lt_u32_e64 s[92:93], v19, v124
	s_nop 1
	v_writelane_b32 v246, s92, 9
	s_nop 1
	v_writelane_b32 v246, s93, 10
	v_cmp_lt_u32_e64 s[92:93], v17, v124
	s_nop 1
	v_writelane_b32 v246, s92, 11
	s_nop 1
	v_writelane_b32 v246, s93, 12
	v_cmp_eq_u32_e64 s[92:93], v19, v124
	v_or_b32_e32 v19, 0x7b, v18
	v_or_b32_e32 v18, 0x7a, v18
	v_writelane_b32 v246, s92, 13
	s_nop 1
	v_writelane_b32 v246, s93, 14
	v_cmp_eq_u32_e64 s[92:93], v17, v124
	s_nop 1
	v_writelane_b32 v246, s92, 15
	s_nop 1
	v_writelane_b32 v246, s93, 16
	v_cmp_lt_u32_e64 s[92:93], v19, v124
	s_nop 1
	v_writelane_b32 v246, s92, 17
	s_nop 1
	v_writelane_b32 v246, s93, 18
	v_cmp_lt_u32_e64 s[92:93], v18, v124
	s_nop 1
	v_writelane_b32 v246, s92, 19
	s_nop 1
	v_writelane_b32 v246, s93, 20
	v_cmp_eq_u32_e64 s[92:93], v19, v124
	v_mov_b32_e32 v19, s81
	s_nop 0
	v_writelane_b32 v246, s92, 21
	s_nop 1
	v_writelane_b32 v246, s93, 22
	v_cmp_eq_u32_e64 s[92:93], v18, v124
	v_or_b32_e32 v18, s80, v116
	v_lshlrev_b64 v[18:19], 8, v[18:19]
	v_or_b32_e32 v18, v18, v126
	v_lshl_add_u64 v[136:137], s[82:83], 0, v[18:19]
	s_lshl_b64 s[80:81], s[80:81], 8
	v_lshlrev_b32_e32 v18, 8, v116
	v_or3_b32 v18, s80, v18, v0
	v_mov_b32_e32 v19, s81
	v_writelane_b32 v246, s92, 23
	v_lshl_add_u64 v[138:139], s[2:3], 0, v[18:19]
	v_mov_b32_e32 v18, s1
	v_writelane_b32 v246, s93, 24
	v_mad_u32_u24 v18, v124, s33, v18
	v_or_b32_e32 v18, v18, v0
	v_writelane_b32 v246, s84, 25
	v_add_u32_e32 v169, 0x2600, v18
	v_writelane_b32 v246, s94, 26
	s_nop 1
	v_writelane_b32 v246, s95, 27

; #define LAS __attribute__((address_space(3)))
; __device__ __forceinline__ float fexp2(float x) { return __builtin_amdgcn_exp2f(x); }
;     __device__ __forceinline__ PT() { out = (float*)(__attribute__((address_space(1))) float*)ptab_get(23); ws = (unsigned char*)(__attribute__((address_space(1))) unsigned char*)ptab_get(24); }
; #define PREFETCH(t) do { \
;         _Pragma("unroll") for (int i_ = 0; i_ < 4; ++i_) { const int pid_ = tid + 512 * i_, row_ = pid_ >> 4, c16_ = pid_ & 15; const unsigned go_ = (tokb + (unsigned)((t) * 128 + row_)) * 2048u + (unsigned)(hd * 128 + 8 * c16_); \
;             preK[i_] = *(const u32x4*)(Kb + go_); preV[i_] = *(const u32x4*)(Vb + go_); } \
;     } while (0)
; __device__ __forceinline__ void attn_unit(const PT& p, LAS unsigned char* lds, int tid, int lane, int wave, int b, int hd, int qb, float lam) {
;     unsigned char* ws = p.ws;
;     const bf16* Qb = (const bf16*)(ws + WS_Q); const bf16* Kb = (const bf16*)(ws + WS_K); const bf16* Vb = (const bf16*)(ws + WS_VV); const bf16* Gb = (const bf16*)((unsigned char*)p.out + DO_G);
;     bf16* Ob = (bf16*)(ws + WS_O);
;     const int r32 = lane & 31, h = lane >> 5, mp = wave >> 2, wq = wave & 3;
;     const int qw0 = qb * 128 + 32 * wq, q = qw0 + r32; const unsigned tokq = (unsigned)(b * SEQ + q), tokb = (unsigned)(b * SEQ);
;     const float slope2 = fexp2(-0.5f * (float)(hd + 1)) * LOG2E;
;     bf16x8 qf[4];
; #pragma unroll
;     for (int ds = 0; ds < 4; ++ds) qf[ds] = ld_frag16(Qb + (tokq * 2048u + (unsigned)(hd * 128 + mp * 64 + 16 * ds + 8 * h)));
;     float mrun = -INFINITY, lsum = 0.f;
;     f32x16 oT[4];
; #pragma unroll
;     for (int db = 0; db < 4; ++db)
; #pragma unroll
;         for (int i = 0; i < 16; ++i) oT[db][i] = 0.f;
;     const int ntiles = qb + 1;
;     u32x4 preV[4], preK[4];
;     ...
;     PREFETCH(0);
;     const LAS unsigned char* kbase0 = lds + A_KOFF + r32 * AK_PITCH + (mp * 64 + 8 * h) * 2;
;     const LAS unsigned char* vbase0 = lds + A_VOFF + (4 * h + ((lane & 15) >> 2)) * AV_PITCH + ((lane >> 4) & 1) * 32 + (lane & 3) * 8;
; __device__ __forceinline__ void phase_attn(const PT& p, LAS unsigned char* lds, int tid, int lane, int wave) {
;     const float s1 = wave_sum(p.in[16][lane] * p.in[17][lane]), s2 = wave_sum(p.in[18][lane] * p.in[19][lane]);
;     const float lam = __expf(s1) - __expf(s2) + LAMBDA_INIT;
.LBB0_1069:
	s_or_b64 exec, exec, s[0:1]
	s_waitcnt lgkmcnt(0)
	v_mov_b32_e32 v0, 0x23eb8
	s_barrier
	ds_read_b64 v[2:3], v0
	v_mov_b32_e32 v0, 0x23ec0
	ds_read_b64 v[6:7], v0
	v_bfe_u32 v0, v196, 8, 1
	v_mul_u32_u24_e32 v0, 0xc0, v0
	v_xor_b32_e32 v0, v196, v0
	v_mov_b32_e32 v1, 0x23e80
	ds_read_b64 v[4:5], v1
	v_mov_b32_e32 v8, 0x23e90
	v_mov_b32_e32 v10, 0x23e98
	ds_read_b64 v[8:9], v8
	ds_read_b64 v[10:11], v10
	s_waitcnt lgkmcnt(2)
	v_readfirstlane_b32 s0, v4
	v_mov_b32_e32 v4, 0x23e88
	v_readfirstlane_b32 s1, v5
	ds_read_b64 v[4:5], v4
	v_and_b32_e32 v198, 63, v0
	v_lshlrev_b32_e32 v1, 2, v198
	s_waitcnt lgkmcnt(2)
	v_readfirstlane_b32 s5, v9
	v_readfirstlane_b32 s4, v8
	s_waitcnt lgkmcnt(0)
	v_readfirstlane_b32 s3, v5
	v_readfirstlane_b32 s2, v4
	v_readfirstlane_b32 s7, v11
	v_readfirstlane_b32 s6, v10
	global_load_dword v4, v1, s[0:1]
	s_nop 1
	global_load_dword v5, v1, s[2:3]
	global_load_dword v8, v1, s[4:5]
	global_load_dword v9, v1, s[6:7]
	v_mbcnt_hi_u32_b32 v1, -1, v182
	v_and_b32_e32 v10, 64, v1
	v_xor_b32_e32 v11, 1, v1
	v_add_u32_e32 v10, 64, v10
	v_cmp_lt_i32_e32 vcc, v11, v10
	v_xor_b32_e32 v12, 2, v1
	v_xor_b32_e32 v13, 4, v1
	v_cndmask_b32_e32 v11, v1, v11, vcc
	v_lshlrev_b32_e32 v11, 2, v11
	v_cmp_lt_i32_e32 vcc, v12, v10
	v_xor_b32_e32 v14, 8, v1
	v_xor_b32_e32 v15, 16, v1
	v_cndmask_b32_e32 v12, v1, v12, vcc
	v_lshlrev_b32_e32 v12, 2, v12
	v_cmp_lt_i32_e32 vcc, v13, v10
	v_xor_b32_e32 v16, 32, v1
	v_readfirstlane_b32 s2, v2
	v_cndmask_b32_e32 v13, v1, v13, vcc
	v_cmp_lt_i32_e32 vcc, v14, v10
	v_readfirstlane_b32 s3, v3
	v_readfirstlane_b32 s0, v7
	v_readfirstlane_b32 s1, v6
	s_cmpk_gt_i32 s90, 0x3ff
	v_readfirstlane_b32 s4, v0
	s_waitcnt vmcnt(2)
	v_mul_f32_e32 v17, v4, v5
	ds_bpermute_b32 v17, v11, v17
	s_waitcnt vmcnt(0)
	v_mul_f32_e32 v18, v8, v9
	ds_bpermute_b32 v11, v11, v18
	s_waitcnt lgkmcnt(1)
	v_fmac_f32_e32 v17, v4, v5
	ds_bpermute_b32 v4, v12, v17
	s_waitcnt lgkmcnt(1)
	v_fmac_f32_e32 v11, v8, v9
	ds_bpermute_b32 v5, v12, v11
	v_lshlrev_b32_e32 v9, 2, v13
	v_cndmask_b32_e32 v8, v1, v14, vcc
	s_waitcnt lgkmcnt(1)
	v_add_f32_e32 v4, v17, v4
	v_lshlrev_b32_e32 v8, 2, v8
	s_waitcnt lgkmcnt(0)
	v_add_f32_e32 v5, v11, v5
	ds_bpermute_b32 v11, v9, v4
	ds_bpermute_b32 v9, v9, v5
	v_cmp_lt_i32_e32 vcc, v15, v10
	s_waitcnt lgkmcnt(1)
	v_add_f32_e32 v4, v4, v11
	s_waitcnt lgkmcnt(0)
	v_add_f32_e32 v5, v5, v9
	ds_bpermute_b32 v9, v8, v4
	ds_bpermute_b32 v8, v8, v5
	v_cndmask_b32_e32 v12, v1, v15, vcc
	v_lshlrev_b32_e32 v179, 2, v12
	v_cmp_lt_i32_e32 vcc, v16, v10
	s_waitcnt lgkmcnt(1)
	v_add_f32_e32 v4, v4, v9
	s_waitcnt lgkmcnt(0)
	v_add_f32_e32 v5, v5, v8
	ds_bpermute_b32 v8, v179, v4
	ds_bpermute_b32 v9, v179, v5
	v_cndmask_b32_e32 v1, v1, v16, vcc
	v_lshlrev_b32_e32 v197, 2, v1
	s_waitcnt lgkmcnt(1)
	v_add_f32_e32 v1, v4, v8
	s_waitcnt lgkmcnt(0)
	v_add_f32_e32 v2, v5, v9
	ds_bpermute_b32 v3, v197, v1
	ds_bpermute_b32 v4, v197, v2
	s_cbranch_scc1 .LBB0_1111
	s_waitcnt lgkmcnt(1)
	v_add_f32_e32 v1, v1, v3
	s_waitcnt lgkmcnt(0)
	v_add_f32_e32 v2, v2, v4
	v_mul_f32_e32 v1, 0x3fb8aa3b, v1
	v_mul_f32_e32 v2, 0x3fb8aa3b, v2
	v_exp_f32_e32 v1, v1
	v_exp_f32_e32 v2, v2
	s_ashr_i32 s36, s4, 6
	s_add_u32 s40, s1, 0x6900000
	s_addc_u32 s41, s0, 0
	v_sub_f32_e32 v1, v1, v2
	s_add_u32 s42, s1, 0x1a900000
	v_lshrrev_b32_e32 v2, 5, v198
	s_addc_u32 s43, s0, 0
	s_ashr_i32 s37, s4, 8
	v_lshlrev_b32_e32 v3, 3, v2
	s_and_b32 s38, s36, 3
	v_lshl_or_b32 v200, s37, 6, v3
	v_lshlrev_b32_e32 v3, 3, v0
	s_add_u32 s44, s1, 0xe900000
	v_and_b32_e32 v201, 0x78, v3
	v_add_u32_e32 v3, 0x200, v0
	s_addc_u32 s45, s0, 0
	v_lshrrev_b32_e32 v203, 4, v3
	v_add_u32_e32 v3, 0x400, v0
	v_add_f32_e32 v199, 0x3eb60549, v1
	v_and_b32_e32 v1, 31, v0
	s_add_u32 s46, s1, 0xa900000
	v_lshrrev_b32_e32 v202, 4, v0
	v_lshrrev_b32_e32 v204, 4, v3
	v_add_u32_e32 v3, 0x600, v0
	v_lshrrev_b32_e32 v4, 2, v0
	v_lshlrev_b32_e32 v0, 4, v0
	s_addc_u32 s47, s0, 0
	s_lshl_b32 s1, s37, 7
	v_lshlrev_b32_e32 v178, 2, v2
	v_and_b32_e32 v0, 0xf0, v0
	v_lshrrev_b32_e32 v205, 4, v3
	s_movk_i32 s0, 0x110
	v_mul_u32_u24_e32 v3, 0x110, v1
	s_add_i32 s1, s1, 0
	v_and_b32_e32 v4, 3, v4
	v_lshl_or_b32 v4, v4, 2, v2
	v_lshlrev_b32_e32 v5, 1, v198
	v_lshlrev_b32_e32 v6, 3, v198
	v_add_u32_e32 v206, 0, v0
	v_lshlrev_b32_e32 v0, 4, v2
	v_and_b32_e32 v5, 32, v5
	v_and_b32_e32 v6, 24, v6
	v_add3_u32 v211, s1, v3, v0
	v_mad_u32_u24 v0, v4, s0, 0
	v_add3_u32 v212, v0, v5, v6
	v_or_b32_e32 v0, 2, v178
	v_cmp_gt_u32_e64 s[6:7], v0, v1
	v_or_b32_e32 v0, 3, v178
	v_cmp_gt_u32_e64 s[8:9], v0, v1
	v_or_b32_e32 v0, 9, v178
	v_cmp_gt_u32_e64 s[12:13], v0, v1
	v_or_b32_e32 v0, 10, v178
	v_cmp_gt_u32_e64 s[14:15], v0, v1
	v_or_b32_e32 v0, 11, v178
	v_cmp_gt_u32_e64 s[16:17], v0, v1
	v_or_b32_e32 v0, 17, v178
	v_cmp_gt_u32_e64 s[20:21], v0, v1
	v_or_b32_e32 v0, 18, v178
	s_cmp_lg_u32 s38, 0
	v_cmp_gt_u32_e64 s[22:23], v0, v1
	v_or_b32_e32 v0, 19, v178
	s_cselect_b64 s[48:49], -1, 0
	s_cmp_eq_u32 s38, 0
	v_cmp_gt_u32_e64 s[24:25], v0, v1
	v_or_b32_e32 v0, 25, v178
	s_cselect_b64 s[50:51], -1, 0
	v_cmp_gt_u32_e64 s[28:29], v0, v1
	v_or_b32_e32 v0, 26, v178
	s_cmp_eq_u32 s38, 1
	v_cmp_gt_u32_e64 s[30:31], v0, v1
	v_or_b32_e32 v0, 27, v178
	s_cselect_b64 s[52:53], -1, 0
	s_cmp_eq_u32 s38, 2
	v_cmp_gt_u32_e64 s[34:35], v0, v1
	v_sub_u32_e64 v0, s38, 1 clamp
	s_cselect_b64 s[54:55], -1, 0
	s_cmp_eq_u32 s38, 3
	v_readfirstlane_b32 s33, v0
	s_cselect_b64 s[56:57], -1, 0
	s_lshl_b32 s39, s38, 14
	v_lshl_or_b32 v0, v205, 11, v201
	v_writelane_b32 v249, s70, 41
	s_add_i32 s86, s39, 0
	v_add_u32_e32 v229, 0x40000, v0
	v_lshl_or_b32 v0, v204, 11, v201
	v_writelane_b32 v249, s71, 42
	s_cmp_eq_u32 s37, 1
; #define LAS __attribute__((address_space(3)))
; #define PREFETCH(t) do { \
;         _Pragma("unroll") for (int i_ = 0; i_ < 4; ++i_) { const int pid_ = tid + 512 * i_, row_ = pid_ >> 4, c16_ = pid_ & 15; const unsigned go_ = (tokb + (unsigned)((t) * 128 + row_)) * 2048u + (unsigned)(hd * 128 + 8 * c16_); \
;             preK[i_] = *(const u32x4*)(Kb + go_); preV[i_] = *(const u32x4*)(Vb + go_); } \
;     } while (0)
; __device__ __forceinline__ void attn_unit(const PT& p, LAS unsigned char* lds, int tid, int lane, int wave, int b, int hd, int qb, float lam) {
;     ...
;     PREFETCH(0);
;     const LAS unsigned char* kbase0 = lds + A_KOFF + r32 * AK_PITCH + (mp * 64 + 8 * h) * 2;
;     const LAS unsigned char* vbase0 = lds + A_VOFF + (4 * h + ((lane & 15) >> 2)) * AV_PITCH + ((lane >> 4) & 1) * 32 + (lane & 3) * 8;
;     ...
;     __syncthreads();
;     STAGE_WRITE(0);
;     asm volatile("" : "+v"(qf[0]), "+v"(qf[1]), "+v"(qf[2]), "+v"(qf[3]));
;     __syncthreads();
; #pragma unroll 1
;     for (int t = 0; t < ntiles; ++t) {
;         const int stg = t & 1;
;         if (t + 1 < ntiles) PREFETCH(t + 1);
;         const LAS unsigned char* kbase = kbase0 + stg * A_STAGE; const LAS unsigned char* vbase = vbase0 + stg * A_STAGE;
;         const bool diag = (t == qb);
; #pragma unroll 2
;         for (int sub = 0; sub < 2; ++sub) {
;             const int nact = diag ? min(2, max(0, wq + 1 - 2 * sub)) : 2;
;             if (nact > 0) {
;                 float sl = slope2; asm volatile("" : "+v"(sl));
;                 const float bq = sl * (float)(t * 128 + sub * 64 + 4 * h - q);
;                 const LAS unsigned char* kb0 = kbase + sub * 64 * AK_PITCH; const LAS unsigned char* vb0 = vbase + sub * 64 * AV_PITCH;
;                 f32x16 s[2];
; #pragma unroll
;                 for (int kb = 0; kb < 2; ++kb) {
;                     if (kb < nact) {
;                         const float bk = bq + sl * (float)(32 * kb);
; #pragma unroll
;                         for (int i = 0; i < 16; ++i) s[kb][i] = __builtin_fmaf(sl, (float)((i & 3) + 8 * (i >> 2)), bk);
	v_add_u32_e32 v230, 0x40000, v0
	v_lshl_or_b32 v0, v203, 11, v201
	v_or_b32_e32 v213, 8, v178
	v_or_b32_e32 v214, 16, v178
	v_or_b32_e32 v215, 24, v178
	s_cselect_b64 s[58:59], -1, 0
	s_cmp_lt_u32 s36, 4
	v_readlane_b32 s36, v249, 0
	v_add_u32_e32 v231, 0x40000, v0
	v_lshl_or_b32 v0, v202, 11, v201
	s_mov_b32 s62, 2.0
	s_mov_b32 s64, 0x41000000
	s_mov_b32 s66, 0x41200000
	s_mov_b32 s68, 0x41800000
	s_mov_b32 s70, 0x41900000
	s_mov_b32 s72, 0x41c00000
	s_mov_b32 s74, 0x41d00000
	v_mul_lo_u32 v207, v202, s0
	v_mul_lo_u32 v208, v203, s0
	v_mul_lo_u32 v209, v204, s0
	v_mul_lo_u32 v210, v205, s0
	v_cmp_gt_u32_e64 s[0:1], v178, v1
	v_cmp_lt_u32_e64 s[4:5], v178, v1
	v_cmp_gt_u32_e64 s[10:11], v213, v1
	v_cmp_gt_u32_e64 s[18:19], v214, v1
	v_cmp_gt_u32_e64 s[26:27], v215, v1
	s_cselect_b64 s[60:61], -1, 0
	v_mov_b32_e32 v51, 0
	v_or_b32_e32 v216, 32, v178
	v_or_b32_e32 v217, 40, v178
	v_or_b32_e32 v218, 48, v178
	v_or_b32_e32 v219, 56, v178
	v_or_b32_e32 v220, 64, v178
	v_or_b32_e32 v221, 0x48, v178
	v_or_b32_e32 v222, 0x50, v178
	v_or_b32_e32 v223, 0x58, v178
	v_or_b32_e32 v224, 0x60, v178
	v_or_b32_e32 v225, 0x68, v178
	v_or_b32_e32 v226, 0x70, v178
	v_or_b32_e32 v227, 0x78, v178
	v_lshl_or_b32 v228, s38, 5, v1
	s_lshl_b32 s38, s90, 4
	s_lshl_b32 s36, s36, 4
	v_add_u32_e32 v232, 0x40000, v0
	s_mov_b32 s63, 0x40400000
	s_mov_b32 s65, 0x41100000
	s_mov_b32 s67, 0x41300000
	s_mov_b32 s69, 0x41880000
	s_mov_b32 s71, 0x41980000
	s_mov_b32 s73, 0x41c80000
	s_mov_b32 s75, 0x41d80000
	s_mov_b32 s89, 0xff800000
	v_mov_b32_e32 v233, 0x23ea0
	v_mov_b32_e32 v234, 0x3727c5ac
	v_mov_b32_e32 v16, 0xff800000
	v_readlane_b32 s37, v249, 1
	v_writelane_b32 v249, s36, 39
	v_bfe_u32 v0, v196, 6, 2
	v_add_u32_e32 v1, 0, v0
	v_cmp_gt_u32_e32 vcc, 34, v1
	v_subrev_u32_e32 v2, 34, v1
	s_nop 1
	v_cndmask_b32_e32 v1, v2, v1, vcc
	v_lshl_add_u32 v3, v1, 6, v198
	v_mul_u32_u24_e32 v4, 0xf10, v3
	v_lshrrev_b32_e32 v4, 16, v4
	v_mul_u32_u24_e32 v5, 17, v4
	v_sub_u32_e32 v5, v3, v5
	v_min_u32_e32 v5, 15, v5
	v_and_b32_e32 v6, 3, v4
	v_bfe_u32 v7, v4, 2, 2
	v_lshl_or_b32 v6, v6, 2, v7
	v_and_b32_e32 v7, 0xfffffff0, v4
	v_or_b32_e32 v6, v7, v6
	v_cndmask_b32_e32 v4, v6, v4, vcc
	v_lshlrev_b32_e32 v4, 12, v4
	v_lshl_add_u32 v229, v5, 4, v4
	v_add_u32_e32 v1, 4, v0
	v_cmp_gt_u32_e32 vcc, 34, v1
	v_subrev_u32_e32 v2, 34, v1
	s_nop 1
	v_cndmask_b32_e32 v1, v2, v1, vcc
	v_lshl_add_u32 v3, v1, 6, v198
	v_mul_u32_u24_e32 v4, 0xf10, v3
	v_lshrrev_b32_e32 v4, 16, v4
	v_mul_u32_u24_e32 v5, 17, v4
	v_sub_u32_e32 v5, v3, v5
	v_min_u32_e32 v5, 15, v5
	v_and_b32_e32 v6, 3, v4
	v_bfe_u32 v7, v4, 2, 2
	v_lshl_or_b32 v6, v6, 2, v7
	v_and_b32_e32 v7, 0xfffffff0, v4
	v_or_b32_e32 v6, v7, v6
	v_cndmask_b32_e32 v4, v6, v4, vcc
	v_lshlrev_b32_e32 v4, 12, v4
	v_lshl_add_u32 v230, v5, 4, v4
	v_add_u32_e32 v1, 8, v0
	v_cmp_gt_u32_e32 vcc, 34, v1
	v_subrev_u32_e32 v2, 34, v1
	s_nop 1
	v_cndmask_b32_e32 v1, v2, v1, vcc
	v_lshl_add_u32 v3, v1, 6, v198
	v_mul_u32_u24_e32 v4, 0xf10, v3
	v_lshrrev_b32_e32 v4, 16, v4
	v_mul_u32_u24_e32 v5, 17, v4
	v_sub_u32_e32 v5, v3, v5
	v_min_u32_e32 v5, 15, v5
	v_and_b32_e32 v6, 3, v4
	v_bfe_u32 v7, v4, 2, 2
	v_lshl_or_b32 v6, v6, 2, v7
	v_and_b32_e32 v7, 0xfffffff0, v4
	v_or_b32_e32 v6, v7, v6
	v_cndmask_b32_e32 v4, v6, v4, vcc
	v_lshlrev_b32_e32 v4, 12, v4
	v_lshl_add_u32 v231, v5, 4, v4
	v_add_u32_e32 v1, 12, v0
	v_cmp_gt_u32_e32 vcc, 34, v1
	v_subrev_u32_e32 v2, 34, v1
	s_nop 1
	v_cndmask_b32_e32 v1, v2, v1, vcc
	v_lshl_add_u32 v3, v1, 6, v198
	v_mul_u32_u24_e32 v4, 0xf10, v3
	v_lshrrev_b32_e32 v4, 16, v4
	v_mul_u32_u24_e32 v5, 17, v4
	v_sub_u32_e32 v5, v3, v5
	v_min_u32_e32 v5, 15, v5
	v_and_b32_e32 v6, 3, v4
	v_bfe_u32 v7, v4, 2, 2
	v_lshl_or_b32 v6, v6, 2, v7
	v_and_b32_e32 v7, 0xfffffff0, v4
	v_or_b32_e32 v6, v7, v6
	v_cndmask_b32_e32 v4, v6, v4, vcc
	v_lshlrev_b32_e32 v4, 12, v4
	v_lshl_add_u32 v232, v5, 4, v4
	v_add_u32_e32 v1, 16, v0
	v_cmp_gt_u32_e32 vcc, 34, v1
	v_subrev_u32_e32 v2, 34, v1
	s_nop 1
	v_cndmask_b32_e32 v1, v2, v1, vcc
	v_lshl_add_u32 v3, v1, 6, v198
	v_mul_u32_u24_e32 v4, 0xf10, v3
	v_lshrrev_b32_e32 v4, 16, v4
	v_mul_u32_u24_e32 v5, 17, v4
	v_sub_u32_e32 v5, v3, v5
	v_min_u32_e32 v5, 15, v5
	v_and_b32_e32 v6, 3, v4
	v_bfe_u32 v7, v4, 2, 2
	v_lshl_or_b32 v6, v6, 2, v7
	v_and_b32_e32 v7, 0xfffffff0, v4
	v_or_b32_e32 v6, v7, v6
	v_cndmask_b32_e32 v4, v6, v4, vcc
	v_lshlrev_b32_e32 v4, 12, v4
	v_lshl_add_u32 v235, v5, 4, v4
	v_add_u32_e32 v1, 20, v0
	v_cmp_gt_u32_e32 vcc, 34, v1
	v_subrev_u32_e32 v2, 34, v1
	s_nop 1
	v_cndmask_b32_e32 v1, v2, v1, vcc
	v_lshl_add_u32 v3, v1, 6, v198
	v_mul_u32_u24_e32 v4, 0xf10, v3
	v_lshrrev_b32_e32 v4, 16, v4
	v_mul_u32_u24_e32 v5, 17, v4
	v_sub_u32_e32 v5, v3, v5
	v_min_u32_e32 v5, 15, v5
	v_and_b32_e32 v6, 3, v4
	v_bfe_u32 v7, v4, 2, 2
	v_lshl_or_b32 v6, v6, 2, v7
	v_and_b32_e32 v7, 0xfffffff0, v4
	v_or_b32_e32 v6, v7, v6
	v_cndmask_b32_e32 v4, v6, v4, vcc
	v_lshlrev_b32_e32 v4, 12, v4
	v_lshl_add_u32 v236, v5, 4, v4
	v_add_u32_e32 v1, 24, v0
	v_cmp_gt_u32_e32 vcc, 34, v1
	v_subrev_u32_e32 v2, 34, v1
	s_nop 1
	v_cndmask_b32_e32 v1, v2, v1, vcc
	v_lshl_add_u32 v3, v1, 6, v198
	v_mul_u32_u24_e32 v4, 0xf10, v3
	v_lshrrev_b32_e32 v4, 16, v4
	v_mul_u32_u24_e32 v5, 17, v4
	v_sub_u32_e32 v5, v3, v5
	v_min_u32_e32 v5, 15, v5
	v_and_b32_e32 v6, 3, v4
	v_bfe_u32 v7, v4, 2, 2
	v_lshl_or_b32 v6, v6, 2, v7
	v_and_b32_e32 v7, 0xfffffff0, v4
	v_or_b32_e32 v6, v7, v6
	v_cndmask_b32_e32 v4, v6, v4, vcc
	v_lshlrev_b32_e32 v4, 12, v4
; #define LAS __attribute__((address_space(3)))
; #define PREFETCH(t) do { \
;         _Pragma("unroll") for (int i_ = 0; i_ < 4; ++i_) { const int pid_ = tid + 512 * i_, row_ = pid_ >> 4, c16_ = pid_ & 15; const unsigned go_ = (tokb + (unsigned)((t) * 128 + row_)) * 2048u + (unsigned)(hd * 128 + 8 * c16_); \
;             preK[i_] = *(const u32x4*)(Kb + go_); preV[i_] = *(const u32x4*)(Vb + go_); } \
;     } while (0)
; __device__ __forceinline__ void attn_unit(const PT& p, LAS unsigned char* lds, int tid, int lane, int wave, int b, int hd, int qb, float lam) {
;     ...
;     PREFETCH(0);
;     const LAS unsigned char* kbase0 = lds + A_KOFF + r32 * AK_PITCH + (mp * 64 + 8 * h) * 2;
;     const LAS unsigned char* vbase0 = lds + A_VOFF + (4 * h + ((lane & 15) >> 2)) * AV_PITCH + ((lane >> 4) & 1) * 32 + (lane & 3) * 8;
	v_lshl_add_u32 v237, v5, 4, v4
	v_add_u32_e32 v1, 28, v0
	v_cmp_gt_u32_e32 vcc, 34, v1
	v_subrev_u32_e32 v2, 34, v1
	s_nop 1
	v_cndmask_b32_e32 v1, v2, v1, vcc
	v_lshl_add_u32 v3, v1, 6, v198
	v_mul_u32_u24_e32 v4, 0xf10, v3
	v_lshrrev_b32_e32 v4, 16, v4
	v_mul_u32_u24_e32 v5, 17, v4
	v_sub_u32_e32 v5, v3, v5
	v_min_u32_e32 v5, 15, v5
	v_and_b32_e32 v6, 3, v4
	v_bfe_u32 v7, v4, 2, 2
	v_lshl_or_b32 v6, v6, 2, v7
	v_and_b32_e32 v7, 0xfffffff0, v4
	v_or_b32_e32 v6, v7, v6
	v_cndmask_b32_e32 v4, v6, v4, vcc
	v_lshlrev_b32_e32 v4, 12, v4
	v_lshl_add_u32 v238, v5, 4, v4
	v_add_u32_e32 v1, 32, v0
	v_cmp_gt_u32_e32 vcc, 34, v1
	v_subrev_u32_e32 v2, 34, v1
	s_nop 1
	v_cndmask_b32_e32 v1, v2, v1, vcc
	v_lshl_add_u32 v3, v1, 6, v198
	v_mul_u32_u24_e32 v4, 0xf10, v3
	v_lshrrev_b32_e32 v4, 16, v4
	v_mul_u32_u24_e32 v5, 17, v4
	v_sub_u32_e32 v5, v3, v5
	v_min_u32_e32 v5, 15, v5
	v_and_b32_e32 v6, 3, v4
	v_bfe_u32 v7, v4, 2, 2
	v_lshl_or_b32 v6, v6, 2, v7
	v_and_b32_e32 v7, 0xfffffff0, v4
	v_or_b32_e32 v6, v7, v6
	v_cndmask_b32_e32 v4, v6, v4, vcc
	v_lshlrev_b32_e32 v4, 12, v4
	v_lshl_add_u32 v206, v5, 4, v4
	v_add_u32_e32 v1, 36, v0
	v_cmp_gt_u32_e32 vcc, 34, v1
	v_subrev_u32_e32 v2, 34, v1
	s_nop 1
	v_cndmask_b32_e32 v1, v2, v1, vcc
	v_lshl_add_u32 v3, v1, 6, v198
	v_mul_u32_u24_e32 v4, 0xf10, v3
	v_lshrrev_b32_e32 v4, 16, v4
	v_mul_u32_u24_e32 v5, 17, v4
	v_sub_u32_e32 v5, v3, v5
	v_min_u32_e32 v5, 15, v5
	v_and_b32_e32 v6, 3, v4
	v_bfe_u32 v7, v4, 2, 2
	v_lshl_or_b32 v6, v6, 2, v7
	v_and_b32_e32 v7, 0xfffffff0, v4
	v_or_b32_e32 v6, v7, v6
	v_cndmask_b32_e32 v4, v6, v4, vcc
	v_lshlrev_b32_e32 v4, 12, v4
	v_lshl_add_u32 v207, v5, 4, v4
	v_add_u32_e32 v1, 40, v0
	v_cmp_gt_u32_e32 vcc, 34, v1
	v_subrev_u32_e32 v2, 34, v1
	s_nop 1
	v_cndmask_b32_e32 v1, v2, v1, vcc
	v_lshl_add_u32 v3, v1, 6, v198
	v_mul_u32_u24_e32 v4, 0xf10, v3
	v_lshrrev_b32_e32 v4, 16, v4
	v_mul_u32_u24_e32 v5, 17, v4
	v_sub_u32_e32 v5, v3, v5
	v_min_u32_e32 v5, 15, v5
	v_and_b32_e32 v6, 3, v4
	v_bfe_u32 v7, v4, 2, 2
	v_lshl_or_b32 v6, v6, 2, v7
	v_and_b32_e32 v7, 0xfffffff0, v4
	v_or_b32_e32 v6, v7, v6
	v_cndmask_b32_e32 v4, v6, v4, vcc
	v_lshlrev_b32_e32 v4, 12, v4
	v_lshl_add_u32 v208, v5, 4, v4
	v_add_u32_e32 v1, 44, v0
	v_cmp_gt_u32_e32 vcc, 34, v1
	v_subrev_u32_e32 v2, 34, v1
	s_nop 1
	v_cndmask_b32_e32 v1, v2, v1, vcc
	v_lshl_add_u32 v3, v1, 6, v198
	v_mul_u32_u24_e32 v4, 0xf10, v3
	v_lshrrev_b32_e32 v4, 16, v4
	v_mul_u32_u24_e32 v5, 17, v4
	v_sub_u32_e32 v5, v3, v5
	v_min_u32_e32 v5, 15, v5
	v_and_b32_e32 v6, 3, v4
	v_bfe_u32 v7, v4, 2, 2
	v_lshl_or_b32 v6, v6, 2, v7
	v_and_b32_e32 v7, 0xfffffff0, v4
	v_or_b32_e32 v6, v7, v6
	v_cndmask_b32_e32 v4, v6, v4, vcc
	v_lshlrev_b32_e32 v4, 12, v4
	v_lshl_add_u32 v209, v5, 4, v4
	v_add_u32_e32 v1, 48, v0
	v_cmp_gt_u32_e32 vcc, 34, v1
	v_subrev_u32_e32 v2, 34, v1
	s_nop 1
	v_cndmask_b32_e32 v1, v2, v1, vcc
	v_lshl_add_u32 v3, v1, 6, v198
	v_mul_u32_u24_e32 v4, 0xf10, v3
	v_lshrrev_b32_e32 v4, 16, v4
	v_mul_u32_u24_e32 v5, 17, v4
	v_sub_u32_e32 v5, v3, v5
	v_min_u32_e32 v5, 15, v5
	v_and_b32_e32 v6, 3, v4
	v_bfe_u32 v7, v4, 2, 2
	v_lshl_or_b32 v6, v6, 2, v7
	v_and_b32_e32 v7, 0xfffffff0, v4
	v_or_b32_e32 v6, v7, v6
	v_cndmask_b32_e32 v4, v6, v4, vcc
	v_lshlrev_b32_e32 v4, 12, v4
	v_lshl_add_u32 v210, v5, 4, v4
	v_add_u32_e32 v1, 52, v0
	v_cmp_gt_u32_e32 vcc, 34, v1
	v_subrev_u32_e32 v2, 34, v1
	s_nop 1
	v_cndmask_b32_e32 v1, v2, v1, vcc
	v_lshl_add_u32 v3, v1, 6, v198
	v_mul_u32_u24_e32 v4, 0xf10, v3
	v_lshrrev_b32_e32 v4, 16, v4
	v_mul_u32_u24_e32 v5, 17, v4
	v_sub_u32_e32 v5, v3, v5
	v_min_u32_e32 v5, 15, v5
	v_and_b32_e32 v6, 3, v4
	v_bfe_u32 v7, v4, 2, 2
	v_lshl_or_b32 v6, v6, 2, v7
	v_and_b32_e32 v7, 0xfffffff0, v4
	v_or_b32_e32 v6, v7, v6
	v_cndmask_b32_e32 v4, v6, v4, vcc
	v_lshlrev_b32_e32 v4, 12, v4
	v_lshl_add_u32 v184, v5, 4, v4
	v_add_u32_e32 v1, 56, v0
	v_cmp_gt_u32_e32 vcc, 34, v1
	v_subrev_u32_e32 v2, 34, v1
	s_nop 1
	v_cndmask_b32_e32 v1, v2, v1, vcc
	v_lshl_add_u32 v3, v1, 6, v198
	v_mul_u32_u24_e32 v4, 0xf10, v3
	v_lshrrev_b32_e32 v4, 16, v4
	v_mul_u32_u24_e32 v5, 17, v4
	v_sub_u32_e32 v5, v3, v5
	v_min_u32_e32 v5, 15, v5
	v_and_b32_e32 v6, 3, v4
	v_bfe_u32 v7, v4, 2, 2
	v_lshl_or_b32 v6, v6, 2, v7
	v_and_b32_e32 v7, 0xfffffff0, v4
	v_or_b32_e32 v6, v7, v6
	v_cndmask_b32_e32 v4, v6, v4, vcc
	v_lshlrev_b32_e32 v4, 12, v4
	v_lshl_add_u32 v185, v5, 4, v4
	v_add_u32_e32 v1, 60, v0
	v_cmp_gt_u32_e32 vcc, 34, v1
	v_subrev_u32_e32 v2, 34, v1
	s_nop 1
	v_cndmask_b32_e32 v1, v2, v1, vcc
	v_lshl_add_u32 v3, v1, 6, v198
	v_mul_u32_u24_e32 v4, 0xf10, v3
	v_lshrrev_b32_e32 v4, 16, v4
	v_mul_u32_u24_e32 v5, 17, v4
	v_sub_u32_e32 v5, v3, v5
	v_min_u32_e32 v5, 15, v5
	v_and_b32_e32 v6, 3, v4
	v_bfe_u32 v7, v4, 2, 2
	v_lshl_or_b32 v6, v6, 2, v7
	v_and_b32_e32 v7, 0xfffffff0, v4
	v_or_b32_e32 v6, v7, v6
	v_cndmask_b32_e32 v4, v6, v4, vcc
	v_lshlrev_b32_e32 v4, 12, v4
	v_lshl_add_u32 v186, v5, 4, v4
	v_add_u32_e32 v1, 64, v0
	v_cmp_gt_u32_e32 vcc, 34, v1
	v_subrev_u32_e32 v2, 34, v1
	s_nop 1
	v_cndmask_b32_e32 v1, v2, v1, vcc
	v_lshl_add_u32 v3, v1, 6, v198
	v_mul_u32_u24_e32 v4, 0xf10, v3
	v_lshrrev_b32_e32 v4, 16, v4
	v_mul_u32_u24_e32 v5, 17, v4
	v_sub_u32_e32 v5, v3, v5
	v_min_u32_e32 v5, 15, v5
	v_and_b32_e32 v6, 3, v4
	v_bfe_u32 v7, v4, 2, 2
	v_lshl_or_b32 v6, v6, 2, v7
	v_and_b32_e32 v7, 0xfffffff0, v4
	v_or_b32_e32 v6, v7, v6
	v_cndmask_b32_e32 v4, v6, v4, vcc
	v_lshlrev_b32_e32 v4, 12, v4
	v_lshl_add_u32 v187, v5, 4, v4
	s_branch .LBB0_1072
